# leader issues its L2/L1 invalidate right after its cross-XCD arrival (all local workgroups already parked) and waits for it before the local release; no invalidate after release
# baseline (speedup 1.0000x reference)
; __device__ __forceinline__ unsigned xb_ld(unsigned* p)              { return __hip_atomic_load(p, __ATOMIC_RELAXED, __HIP_MEMORY_SCOPE_AGENT); }
; __device__ __forceinline__ unsigned xb_add(unsigned* p, unsigned v) { return __hip_atomic_fetch_add(p, v, __ATOMIC_RELAXED, __HIP_MEMORY_SCOPE_AGENT); }
; #define XB_SPIN(cond, bar) do { unsigned _sp = 0; while (cond) { __builtin_amdgcn_s_sleep(1); \
;     if ((++_sp & 255u) == 0u) { if (xb_ld(&(bar)[XB_TMO])) break; if (_sp > XB_SPIN_CAP) { atomicAdd(&(bar)[XB_TMO], 1u); break; } } } } while (0)
; __device__ __forceinline__ void xcd_barrier(const XcdBarrier& b) {
;     ...
;         const unsigned old = xb_add(&bar[XB_XSUB(b.x)], 1u);
;         const unsigned gen = old / nloc;
;         if (old + 1u == (gen + 1u) * nloc) {
;             __builtin_amdgcn_fence(__ATOMIC_RELEASE, "agent");
;             asm volatile("s_waitcnt vmcnt(0)" ::: "memory");
;             const unsigned og = xb_add(&bar[XB_TOP], 1u);
;             const unsigned tg = og / nx;
;             if (og + 1u == (tg + 1u) * nx) xb_add(&bar[XB_TOPGEN], 1u);
;             else XB_SPIN(xb_ld(&bar[XB_TOPGEN]) == tg, bar);
;             __builtin_amdgcn_fence(__ATOMIC_ACQUIRE, "agent");
;             xb_add(&bar[XB_XGEN(b.x)], 1u);
;             asm volatile("s_waitcnt vmcnt(0)" ::: "memory");
.LBB0_14:
	s_or_b64 exec, exec, s[8:9]
	v_mov_b32_e32 v0, 0x2000
	s_waitcnt vmcnt(0)
	global_atomic_add v0, v183, s[6:7] offset:1024

; __device__ __forceinline__ unsigned xb_ld(unsigned* p)              { return __hip_atomic_load(p, __ATOMIC_RELAXED, __HIP_MEMORY_SCOPE_AGENT); }
; __device__ __forceinline__ unsigned xb_add(unsigned* p, unsigned v) { return __hip_atomic_fetch_add(p, v, __ATOMIC_RELAXED, __HIP_MEMORY_SCOPE_AGENT); }
; #define XB_SPIN(cond, bar) do { unsigned _sp = 0; while (cond) { __builtin_amdgcn_s_sleep(1); \
;     if ((++_sp & 255u) == 0u) { if (xb_ld(&(bar)[XB_TMO])) break; if (_sp > XB_SPIN_CAP) { atomicAdd(&(bar)[XB_TMO], 1u); break; } } } } while (0)
; __device__ __forceinline__ void xcd_barrier(const XcdBarrier& b) {
;     ...
;             asm volatile("s_waitcnt vmcnt(0)" ::: "memory");
;             const unsigned og = xb_add(&bar[XB_TOP], 1u);
;             const unsigned tg = og / nx;
;             if (og + 1u == (tg + 1u) * nx) xb_add(&bar[XB_TOPGEN], 1u);
;             else XB_SPIN(xb_ld(&bar[XB_TOPGEN]) == tg, bar);
;             __builtin_amdgcn_fence(__ATOMIC_ACQUIRE, "agent");
.LBB0_866:
	s_or_b64 exec, exec, s[10:11]
	buffer_inv sc1
	s_waitcnt vmcnt(1)
	v_readfirstlane_b32 s2, v2
	v_cvt_f32_u32_e32 v2, v0
	v_sub_u32_e32 v3, 0, v0
	v_add_u32_e32 v1, s2, v1
	v_readlane_b32 s2, v254, 6
	v_rcp_iflag_f32_e32 v2, v2
	v_readlane_b32 s3, v254, 7
	s_mov_b64 s[10:11], -1
	v_mul_f32_e32 v2, 0x4f7ffffe, v2
	v_cvt_u32_f32_e32 v2, v2
	v_mul_lo_u32 v3, v3, v2
	v_mul_hi_u32 v3, v2, v3
	v_add_u32_e32 v2, v2, v3
	v_mul_hi_u32 v2, v1, v2
	v_mul_lo_u32 v3, v2, v0
	v_sub_u32_e32 v3, v1, v3
	v_cmp_ge_u32_e32 vcc, v3, v0
	v_add_u32_e32 v4, 1, v2
	v_add_u32_e32 v1, 1, v1
	v_cndmask_b32_e32 v2, v2, v4, vcc
	v_sub_u32_e32 v4, v3, v0
	v_cndmask_b32_e32 v3, v3, v4, vcc
	v_cmp_ge_u32_e32 vcc, v3, v0
	v_add_u32_e32 v3, 1, v2
	s_nop 0
	v_cndmask_b32_e32 v2, v2, v3, vcc
	v_mul_lo_u32 v3, v0, v2
	v_add_u32_e32 v0, v3, v0
	v_cmp_ne_u32_e32 vcc, v1, v0
	v_mov_b64_e32 v[0:1], s[2:3]
	s_and_saveexec_b64 s[8:9], vcc
	s_cbranch_execz .LBB0_878
	v_readlane_b32 s2, v254, 6
	v_readlane_b32 s3, v254, 7
	s_mov_b64 s[12:13], 0
	s_nop 3
	global_load_dword v0, v113, s[2:3] sc1
	s_waitcnt vmcnt(0)
	v_cmp_eq_u32_e32 vcc, v0, v2
	s_and_saveexec_b64 s[10:11], vcc
	s_cbranch_execz .LBB0_877
	s_mov_b32 s2, 1
	s_branch .LBB0_870
